# DOWN: epilogue inputs (PRE rows, STAT) touched from inside the K loop three iterations before the end so the epilogue loads hit L2
# baseline (speedup 1.0000x reference)
; #define PG8_STAGE(bufoff, gbase, voff) do { _Pragma("unroll") for (int _i = 0; _i < 2; ++_i) \
;         __builtin_amdgcn_global_load_lds((const unsigned*)((const char*)(gbase) + (voff)[_i]), (LAS unsigned*)(lds + (bufoff) + ldsw + _i * 8192), 16, 0, 0); } while (0)
; #define PG8_LDA(dst, b, h) do { _Pragma("unroll") for (int m = 0; m < 4; ++m) _Pragma("unroll") for (int k = 0; k < 2; ++k) dst[m][k] = *(const LAS bf16x8*)(lds + PG8_SA(b, h) + aoff + m * 2048 + k * 1024); } while (0)
; #define PG8_LDB(dst, b, h) do { _Pragma("unroll") for (int n = 0; n < 2; ++n) _Pragma("unroll") for (int k = 0; k < 2; ++k) dst[n][k] = *(const LAS bf16x8*)(lds + PG8_SB(b, h) + boff + n * 2048 + k * 1024); } while (0)
; #define PG8_WAIT_V(n) asm volatile("s_waitcnt vmcnt(" #n ")" ::: "memory")
; #define PG8_BAR __builtin_amdgcn_s_barrier()
; template <class Epi, class Sched>
; __device__ __forceinline__ void gemm_phase(LAS unsigned char* lds, const Gemm g, const Sched& S, const Epi& E) {
;     ...
;             PG8_LDB(B0, 0, 0); PG8_LDB(B1, 0, 1); PG8_SCHED; PG8_LDA(At, 0, 0); PG8_STAGE(PG8_SA(1, 1), a1 + hA, voffA);
;             PG8_WAIT_V(8); PG8_WAIT_L(0); PG8_BAR; PG8_MMA(0, 0, At, B0); PG8_MMA(0, 1, At, B1); PG8_BAR; PG8_SCHED;
;             PG8_LDA(At, 0, 1); PG8_STAGE(PG8_SB(0, 0), b2, voffB); PG8_STAGE(PG8_SB(0, 1), b2 + hB, voffB); PG8_STAGE(PG8_SA(0, 0), a2, voffA);
;             PG8_WAIT_V(8); PG8_WAIT_L(0); PG8_BAR; PG8_MMA(1, 0, At, B0); PG8_MMA(1, 1, At, B1); PG8_BAR; PG8_SCHED;
;             PG8_LDB(B0, 1, 0); PG8_LDB(B1, 1, 1); PG8_SCHED; PG8_LDA(At, 1, 0); PG8_STAGE(PG8_SA(0, 1), a2 + hA, voffA);
;             PG8_WAIT_V(8); PG8_WAIT_L(0); PG8_BAR; PG8_MMA(0, 0, At, B0); PG8_MMA(0, 1, At, B1); PG8_BAR; PG8_SCHED;
;             PG8_LDA(At, 1, 1); PG8_STAGE(PG8_SB(1, 0), b3, voffB); PG8_STAGE(PG8_SB(1, 1), b3 + hB, voffB); PG8_STAGE(PG8_SA(1, 0), a3, voffA);
;             PG8_WAIT_V(8); PG8_WAIT_L(0); PG8_BAR; PG8_MMA(1, 0, At, B0); PG8_MMA(1, 1, At, B1); PG8_BAR; PG8_SCHED;
;     __device__ __forceinline__ void operator()(Acc& acc, const Unit& u, int wr, int wc, int fr, int fq) const {
;     ...
;                 for (int m = 0; m < 2; ++m) { const int row = row0 + ai * HALF + (mp + m) * 16; ms[m] = st[row];
; #pragma unroll
;                     for (int bj = 0; bj < 2; ++bj) rr[m][bj] = *(const h16x8*)(pre + (size_t)row * DM + colb + bj * BJ); }
.LBB0_1048:
	s_add_u32 s2, s20, 0x200
	s_addc_u32 s3, s21, 0
	s_add_i32 s47, 0, 0x10000
	s_cmpk_eq_i32 s46, 0x54
	s_cselect_b32 s25, s5, s3
	s_cselect_b32 s24, s4, s2
	s_cselect_b32 s23, s19, s43
	s_cselect_b32 s22, s18, s42
	s_add_i32 s48, 0, 0x14000
	v_add_u32_e32 v154, s47, v221
	v_add_u32_e32 v178, s48, v221
	ds_read_b128 v[132:135], v154
	ds_read_b128 v[136:139], v154 offset:1024
	ds_read_b128 v[140:143], v154 offset:2048
	ds_read_b128 v[154:157], v154 offset:3072
	ds_read_b128 v[166:169], v178
	ds_read_b128 v[170:173], v178 offset:1024
	ds_read_b128 v[174:177], v178 offset:2048
	ds_read_b128 v[178:181], v178 offset:3072
	v_lshl_add_u64 v[226:227], s[20:21], 0, v[162:163]
	s_add_i32 m0, s29, 0xc000
	ds_read_b128 v[182:185], v224
	ds_read_b128 v[186:189], v224 offset:1024
	ds_read_b128 v[190:193], v224 offset:2048
	ds_read_b128 v[194:197], v224 offset:3072
	ds_read_b128 v[198:201], v224 offset:4096
	ds_read_b128 v[202:205], v224 offset:5120
	ds_read_b128 v[206:209], v224 offset:6144
	ds_read_b128 v[210:213], v224 offset:7168
	global_load_lds_dwordx4 v[226:227], off
	v_lshl_add_u64 v[226:227], s[20:21], 0, v[164:165]
	s_add_i32 m0, s29, 0xe000
	s_nop 0
	global_load_lds_dwordx4 v[226:227], off
	s_cmpk_lg_i32 s46, 0x50
	s_cbranch_scc1 .Ldn_kt_skip
	v_bfe_u32 v236, v223, 3, 2
	v_lshl_or_b32 v236, v236, 4, v220
	s_lshl_b32 s100, s41, 8
	s_add_i32 s100, s100, s35
	v_add_u32_e32 v236, s100, v236
	v_lshl_or_b32 v237, s10, 8, v223
	v_lshlrev_b32_e32 v237, 1, v237
	v_lshl_add_u32 v237, v236, 12, v237
	v_lshlrev_b32_e32 v238, 3, v236
	global_load_dword v255, v237, s[88:89]
	v_add_u32_e32 v237, 0x80000, v237
	global_load_dword v255, v238, s[66:67]
	global_load_dword v255, v237, s[88:89]
	global_load_dword v255, v238, s[66:67] offset:1024
.Ldn_kt_skip:
	s_waitcnt vmcnt(8)
	s_waitcnt lgkmcnt(0)
	s_barrier
	s_setprio 1
	s_waitcnt lgkmcnt(0)
	v_mfma_f32_16x16x32_bf16 v[128:131], v[132:135], v[182:185], v[128:131]
	v_mfma_f32_16x16x32_bf16 v[124:127], v[140:143], v[182:185], v[124:127]
	v_mfma_f32_16x16x32_bf16 v[112:115], v[132:135], v[190:193], v[112:115]
	v_mfma_f32_16x16x32_bf16 v[108:111], v[140:143], v[190:193], v[108:111]
	v_mfma_f32_16x16x32_bf16 v[94:97], v[132:135], v[198:201], v[94:97]
	v_mfma_f32_16x16x32_bf16 v[90:93], v[140:143], v[198:201], v[90:93]
	v_mfma_f32_16x16x32_bf16 v[78:81], v[132:135], v[206:209], v[78:81]
	v_mfma_f32_16x16x32_bf16 v[74:77], v[140:143], v[206:209], v[74:77]
	v_mfma_f32_16x16x32_bf16 v[128:131], v[136:139], v[186:189], v[128:131]
	v_mfma_f32_16x16x32_bf16 v[124:127], v[154:157], v[186:189], v[124:127]
	v_mfma_f32_16x16x32_bf16 v[112:115], v[136:139], v[194:197], v[112:115]
	v_mfma_f32_16x16x32_bf16 v[108:111], v[154:157], v[194:197], v[108:111]
	v_mfma_f32_16x16x32_bf16 v[94:97], v[136:139], v[202:205], v[94:97]
	v_mfma_f32_16x16x32_bf16 v[90:93], v[154:157], v[202:205], v[90:93]
	v_mfma_f32_16x16x32_bf16 v[78:81], v[136:139], v[210:213], v[78:81]
	v_mfma_f32_16x16x32_bf16 v[74:77], v[154:157], v[210:213], v[74:77]
	s_setprio 0
	s_setprio 1
	v_mfma_f32_16x16x32_bf16 v[120:123], v[166:169], v[182:185], v[120:123]
	v_mfma_f32_16x16x32_bf16 v[116:119], v[174:177], v[182:185], v[116:119]
	v_mfma_f32_16x16x32_bf16 v[104:107], v[166:169], v[190:193], v[104:107]
	v_mfma_f32_16x16x32_bf16 v[100:103], v[174:177], v[190:193], v[100:103]
	v_mfma_f32_16x16x32_bf16 v[86:89], v[166:169], v[198:201], v[86:89]
	v_mfma_f32_16x16x32_bf16 v[82:85], v[174:177], v[198:201], v[82:85]
	v_mfma_f32_16x16x32_bf16 v[70:73], v[166:169], v[206:209], v[70:73]
	v_mfma_f32_16x16x32_bf16 v[66:69], v[174:177], v[206:209], v[66:69]
	v_mfma_f32_16x16x32_bf16 v[120:123], v[170:173], v[186:189], v[120:123]
	v_mfma_f32_16x16x32_bf16 v[116:119], v[178:181], v[186:189], v[116:119]
	v_mfma_f32_16x16x32_bf16 v[104:107], v[170:173], v[194:197], v[104:107]
	v_mfma_f32_16x16x32_bf16 v[100:103], v[178:181], v[194:197], v[100:103]
	v_mfma_f32_16x16x32_bf16 v[86:89], v[170:173], v[202:205], v[86:89]
	v_mfma_f32_16x16x32_bf16 v[82:85], v[178:181], v[202:205], v[82:85]
	v_mfma_f32_16x16x32_bf16 v[70:73], v[170:173], v[210:213], v[70:73]
	v_mfma_f32_16x16x32_bf16 v[66:69], v[178:181], v[210:213], v[66:69]
	s_setprio 0
	s_barrier
	s_add_i32 s20, s47, s28
	v_lshl_add_u64 v[226:227], s[22:23], 0, v[158:159]
	s_mov_b32 m0, s20
	ds_read_b128 v[182:185], v224 offset:16384
	ds_read_b128 v[186:189], v224 offset:17408
	ds_read_b128 v[190:193], v224 offset:18432
	ds_read_b128 v[194:197], v224 offset:19456
	ds_read_b128 v[198:201], v224 offset:20480
	ds_read_b128 v[202:205], v224 offset:21504
	ds_read_b128 v[206:209], v224 offset:22528
	ds_read_b128 v[210:213], v224 offset:23552
	global_load_lds_dwordx4 v[226:227], off
	s_add_i32 m0, s20, 0x2000
	s_add_u32 s20, s22, 0x58000
	v_lshl_add_u64 v[228:229], s[22:23], 0, v[144:145]
	s_addc_u32 s21, s23, 0
	s_add_i32 s47, s48, s28
	global_load_lds_dwordx4 v[228:229], off
	v_lshl_add_u64 v[230:231], s[20:21], 0, v[158:159]
	s_mov_b32 m0, s47
	v_lshl_add_u64 v[232:233], s[24:25], 0, v[146:147]
	global_load_lds_dwordx4 v[230:231], off
	v_lshl_add_u64 v[230:231], s[20:21], 0, v[144:145]
	s_add_i32 m0, s47, 0x2000
	s_nop 0
	global_load_lds_dwordx4 v[230:231], off
	v_lshl_add_u64 v[230:231], s[24:25], 0, v[160:161]
	s_mov_b32 m0, s29
	s_nop 0
	global_load_lds_dwordx4 v[230:231], off
	s_mov_b32 m0, s30
	s_nop 0
	global_load_lds_dwordx4 v[232:233], off
	s_waitcnt vmcnt(8)
	s_waitcnt lgkmcnt(0)
	s_barrier
; #define PG8_STAGE(bufoff, gbase, voff) do { _Pragma("unroll") for (int _i = 0; _i < 2; ++_i) \
;         __builtin_amdgcn_global_load_lds((const unsigned*)((const char*)(gbase) + (voff)[_i]), (LAS unsigned*)(lds + (bufoff) + ldsw + _i * 8192), 16, 0, 0); } while (0)
; #define PG8_LDA(dst, b, h) do { _Pragma("unroll") for (int m = 0; m < 4; ++m) _Pragma("unroll") for (int k = 0; k < 2; ++k) dst[m][k] = *(const LAS bf16x8*)(lds + PG8_SA(b, h) + aoff + m * 2048 + k * 1024); } while (0)
; #define PG8_LDB(dst, b, h) do { _Pragma("unroll") for (int n = 0; n < 2; ++n) _Pragma("unroll") for (int k = 0; k < 2; ++k) dst[n][k] = *(const LAS bf16x8*)(lds + PG8_SB(b, h) + boff + n * 2048 + k * 1024); } while (0)
; #define PG8_MMA(ai, bj, At, Bt) do { __builtin_amdgcn_s_setprio(1); _Pragma("unroll") for (int m = 0; m < 4; ++m) _Pragma("unroll") for (int n = 0; n < 2; ++n) _Pragma("unroll") for (int k = 0; k < 2; ++k) \
;         acc[ai][bj][m][n] = __builtin_amdgcn_mfma_f32_16x16x32_bf16(Bt[n][k], At[m][k], acc[ai][bj][m][n], 0, 0, 0); __builtin_amdgcn_s_setprio(0); } while (0)
; #define PG8_WAIT_V(n) asm volatile("s_waitcnt vmcnt(" #n ")" ::: "memory")
; #define PG8_WAIT_L(n) asm volatile("s_waitcnt lgkmcnt(" #n ")" ::: "memory")
; #define PG8_BAR __builtin_amdgcn_s_barrier()
; #define PG8_SCHED __builtin_amdgcn_sched_barrier(0)
; template <class Epi, class Sched>
; __device__ __forceinline__ void gemm_phase(LAS unsigned char* lds, const Gemm g, const Sched& S, const Epi& E) {
;     ...
;             PG8_WAIT_V(8); PG8_WAIT_L(0); PG8_BAR; PG8_MMA(1, 0, At, B0); PG8_MMA(1, 1, At, B1); PG8_BAR; PG8_SCHED;
;             PG8_LDB(B0, 1, 0); PG8_LDB(B1, 1, 1); PG8_SCHED; PG8_LDA(At, 1, 0); PG8_STAGE(PG8_SA(0, 1), a2 + hA, voffA);
;             PG8_WAIT_V(8); PG8_WAIT_L(0); PG8_BAR; PG8_MMA(0, 0, At, B0); PG8_MMA(0, 1, At, B1); PG8_BAR; PG8_SCHED;
;             PG8_LDA(At, 1, 1); PG8_STAGE(PG8_SB(1, 0), b3, voffB); PG8_STAGE(PG8_SB(1, 1), b3 + hB, voffB); PG8_STAGE(PG8_SA(1, 0), a3, voffA);
;             PG8_WAIT_V(8); PG8_WAIT_L(0); PG8_BAR; PG8_MMA(1, 0, At, B0); PG8_MMA(1, 1, At, B1); PG8_BAR; PG8_SCHED;
	s_setprio 1
	s_waitcnt lgkmcnt(0)
	v_mfma_f32_16x16x32_bf16 v[62:65], v[132:135], v[182:185], v[62:65]
	v_mfma_f32_16x16x32_bf16 v[58:61], v[140:143], v[182:185], v[58:61]
	v_mfma_f32_16x16x32_bf16 v[46:49], v[132:135], v[190:193], v[46:49]
	v_mfma_f32_16x16x32_bf16 v[42:45], v[140:143], v[190:193], v[42:45]
	v_mfma_f32_16x16x32_bf16 v[30:33], v[132:135], v[198:201], v[30:33]
	v_mfma_f32_16x16x32_bf16 v[26:29], v[140:143], v[198:201], v[26:29]
	v_mfma_f32_16x16x32_bf16 v[14:17], v[132:135], v[206:209], v[14:17]
	v_mfma_f32_16x16x32_bf16 v[10:13], v[140:143], v[206:209], v[10:13]
	v_mfma_f32_16x16x32_bf16 v[62:65], v[136:139], v[186:189], v[62:65]
	v_mfma_f32_16x16x32_bf16 v[58:61], v[154:157], v[186:189], v[58:61]
	v_mfma_f32_16x16x32_bf16 v[46:49], v[136:139], v[194:197], v[46:49]
	v_mfma_f32_16x16x32_bf16 v[42:45], v[154:157], v[194:197], v[42:45]
	v_mfma_f32_16x16x32_bf16 v[30:33], v[136:139], v[202:205], v[30:33]
	v_mfma_f32_16x16x32_bf16 v[26:29], v[154:157], v[202:205], v[26:29]
	v_mfma_f32_16x16x32_bf16 v[14:17], v[136:139], v[210:213], v[14:17]
	v_mfma_f32_16x16x32_bf16 v[10:13], v[154:157], v[210:213], v[10:13]
	s_setprio 0
	s_setprio 1
	v_mfma_f32_16x16x32_bf16 v[54:57], v[166:169], v[182:185], v[54:57]
	v_mfma_f32_16x16x32_bf16 v[50:53], v[174:177], v[182:185], v[50:53]
	v_mfma_f32_16x16x32_bf16 v[38:41], v[166:169], v[190:193], v[38:41]
	v_mfma_f32_16x16x32_bf16 v[34:37], v[174:177], v[190:193], v[34:37]
	v_mfma_f32_16x16x32_bf16 v[22:25], v[166:169], v[198:201], v[22:25]
	v_mfma_f32_16x16x32_bf16 v[18:21], v[174:177], v[198:201], v[18:21]
	v_mfma_f32_16x16x32_bf16 v[6:9], v[166:169], v[206:209], v[6:9]
	v_mfma_f32_16x16x32_bf16 v[2:5], v[174:177], v[206:209], v[2:5]
	v_mfma_f32_16x16x32_bf16 v[54:57], v[170:173], v[186:189], v[54:57]
	v_mfma_f32_16x16x32_bf16 v[50:53], v[178:181], v[186:189], v[50:53]
	v_mfma_f32_16x16x32_bf16 v[38:41], v[170:173], v[194:197], v[38:41]
	v_mfma_f32_16x16x32_bf16 v[34:37], v[178:181], v[194:197], v[34:37]
	v_mfma_f32_16x16x32_bf16 v[22:25], v[170:173], v[202:205], v[22:25]
	v_mfma_f32_16x16x32_bf16 v[18:21], v[178:181], v[202:205], v[18:21]
	v_mfma_f32_16x16x32_bf16 v[6:9], v[170:173], v[210:213], v[6:9]
	v_mfma_f32_16x16x32_bf16 v[2:5], v[178:181], v[210:213], v[2:5]
	s_setprio 0
	s_barrier
	s_add_i32 s47, 0, 0x18000
	s_add_i32 s48, 0, 0x1c000
	v_add_u32_e32 v154, s47, v221
	v_add_u32_e32 v178, s48, v221
	ds_read_b128 v[132:135], v154
	ds_read_b128 v[136:139], v154 offset:1024
	ds_read_b128 v[140:143], v154 offset:2048
	ds_read_b128 v[154:157], v154 offset:3072
	ds_read_b128 v[166:169], v178
	ds_read_b128 v[170:173], v178 offset:1024
	ds_read_b128 v[174:177], v178 offset:2048
	ds_read_b128 v[178:181], v178 offset:3072
	s_add_u32 s20, s24, 0x160000
	s_addc_u32 s21, s25, 0
	s_mov_b32 m0, s31
	v_lshl_add_u64 v[234:235], s[20:21], 0, v[160:161]
	ds_read_b128 v[182:185], v224 offset:32768
	ds_read_b128 v[186:189], v224 offset:33792
	ds_read_b128 v[190:193], v224 offset:34816
	ds_read_b128 v[194:197], v224 offset:35840
	ds_read_b128 v[198:201], v224 offset:36864
	ds_read_b128 v[202:205], v224 offset:37888
	ds_read_b128 v[206:209], v224 offset:38912
	ds_read_b128 v[210:213], v224 offset:39936
	global_load_lds_dwordx4 v[234:235], off
	v_lshl_add_u64 v[234:235], s[20:21], 0, v[146:147]
	s_mov_b32 m0, s34
	s_nop 0
	global_load_lds_dwordx4 v[234:235], off
	s_waitcnt vmcnt(8)
	s_waitcnt lgkmcnt(0)
	s_barrier
	s_setprio 1
	s_waitcnt lgkmcnt(0)
	v_mfma_f32_16x16x32_bf16 v[128:131], v[132:135], v[182:185], v[128:131]
	v_mfma_f32_16x16x32_bf16 v[124:127], v[140:143], v[182:185], v[124:127]
	v_mfma_f32_16x16x32_bf16 v[112:115], v[132:135], v[190:193], v[112:115]
	v_mfma_f32_16x16x32_bf16 v[108:111], v[140:143], v[190:193], v[108:111]
	v_mfma_f32_16x16x32_bf16 v[94:97], v[132:135], v[198:201], v[94:97]
	v_mfma_f32_16x16x32_bf16 v[90:93], v[140:143], v[198:201], v[90:93]
	v_mfma_f32_16x16x32_bf16 v[78:81], v[132:135], v[206:209], v[78:81]
	v_mfma_f32_16x16x32_bf16 v[74:77], v[140:143], v[206:209], v[74:77]
	v_mfma_f32_16x16x32_bf16 v[128:131], v[136:139], v[186:189], v[128:131]
	v_mfma_f32_16x16x32_bf16 v[124:127], v[154:157], v[186:189], v[124:127]
	v_mfma_f32_16x16x32_bf16 v[112:115], v[136:139], v[194:197], v[112:115]
	v_mfma_f32_16x16x32_bf16 v[108:111], v[154:157], v[194:197], v[108:111]
	v_mfma_f32_16x16x32_bf16 v[94:97], v[136:139], v[202:205], v[94:97]
	v_mfma_f32_16x16x32_bf16 v[90:93], v[154:157], v[202:205], v[90:93]
	v_mfma_f32_16x16x32_bf16 v[78:81], v[136:139], v[210:213], v[78:81]
	v_mfma_f32_16x16x32_bf16 v[74:77], v[154:157], v[210:213], v[74:77]
	s_setprio 0
	s_setprio 1
	v_mfma_f32_16x16x32_bf16 v[120:123], v[166:169], v[182:185], v[120:123]
	v_mfma_f32_16x16x32_bf16 v[116:119], v[174:177], v[182:185], v[116:119]
	v_mfma_f32_16x16x32_bf16 v[104:107], v[166:169], v[190:193], v[104:107]
	v_mfma_f32_16x16x32_bf16 v[100:103], v[174:177], v[190:193], v[100:103]
	v_mfma_f32_16x16x32_bf16 v[86:89], v[166:169], v[198:201], v[86:89]
	v_mfma_f32_16x16x32_bf16 v[82:85], v[174:177], v[198:201], v[82:85]
	v_mfma_f32_16x16x32_bf16 v[70:73], v[166:169], v[206:209], v[70:73]
	v_mfma_f32_16x16x32_bf16 v[66:69], v[174:177], v[206:209], v[66:69]
	v_mfma_f32_16x16x32_bf16 v[120:123], v[170:173], v[186:189], v[120:123]
	v_mfma_f32_16x16x32_bf16 v[116:119], v[178:181], v[186:189], v[116:119]
	v_mfma_f32_16x16x32_bf16 v[104:107], v[170:173], v[194:197], v[104:107]
	v_mfma_f32_16x16x32_bf16 v[100:103], v[178:181], v[194:197], v[100:103]
	v_mfma_f32_16x16x32_bf16 v[86:89], v[170:173], v[202:205], v[86:89]
	v_mfma_f32_16x16x32_bf16 v[82:85], v[178:181], v[202:205], v[82:85]
	v_mfma_f32_16x16x32_bf16 v[70:73], v[170:173], v[210:213], v[70:73]
	v_mfma_f32_16x16x32_bf16 v[66:69], v[178:181], v[210:213], v[66:69]
	s_setprio 0
	s_barrier
; #define PG8_STAGE(bufoff, gbase, voff) do { _Pragma("unroll") for (int _i = 0; _i < 2; ++_i) \
;         __builtin_amdgcn_global_load_lds((const unsigned*)((const char*)(gbase) + (voff)[_i]), (LAS unsigned*)(lds + (bufoff) + ldsw + _i * 8192), 16, 0, 0); } while (0)
; #define PG8_LDA(dst, b, h) do { _Pragma("unroll") for (int m = 0; m < 4; ++m) _Pragma("unroll") for (int k = 0; k < 2; ++k) dst[m][k] = *(const LAS bf16x8*)(lds + PG8_SA(b, h) + aoff + m * 2048 + k * 1024); } while (0)
; #define PG8_MMA(ai, bj, At, Bt) do { __builtin_amdgcn_s_setprio(1); _Pragma("unroll") for (int m = 0; m < 4; ++m) _Pragma("unroll") for (int n = 0; n < 2; ++n) _Pragma("unroll") for (int k = 0; k < 2; ++k) \
;         acc[ai][bj][m][n] = __builtin_amdgcn_mfma_f32_16x16x32_bf16(Bt[n][k], At[m][k], acc[ai][bj][m][n], 0, 0, 0); __builtin_amdgcn_s_setprio(0); } while (0)
; #define PG8_WAIT_V(n) asm volatile("s_waitcnt vmcnt(" #n ")" ::: "memory")
; #define PG8_WAIT_L(n) asm volatile("s_waitcnt lgkmcnt(" #n ")" ::: "memory")
; #define PG8_BAR __builtin_amdgcn_s_barrier()
; #define PG8_SCHED __builtin_amdgcn_sched_barrier(0)
; template <class Epi, class Sched>
; __device__ __forceinline__ void gemm_phase(LAS unsigned char* lds, const Gemm g, const Sched& S, const Epi& E) {
;     ...
;             PG8_LDA(At, 1, 1); PG8_STAGE(PG8_SB(1, 0), b3, voffB); PG8_STAGE(PG8_SB(1, 1), b3 + hB, voffB); PG8_STAGE(PG8_SA(1, 0), a3, voffA);
;             PG8_WAIT_V(8); PG8_WAIT_L(0); PG8_BAR; PG8_MMA(1, 0, At, B0); PG8_MMA(1, 1, At, B1); PG8_BAR; PG8_SCHED;
;         }
	s_add_i32 s20, s47, s28
	v_lshl_add_u64 v[226:227], v[226:227], 0, s[76:77]
	s_mov_b32 m0, s20
	ds_read_b128 v[182:185], v224 offset:49152
	ds_read_b128 v[186:189], v224 offset:50176
	ds_read_b128 v[190:193], v224 offset:51200
	ds_read_b128 v[194:197], v224 offset:52224
	ds_read_b128 v[198:201], v224 offset:53248
	ds_read_b128 v[202:205], v224 offset:54272
	ds_read_b128 v[206:209], v224 offset:55296
	ds_read_b128 v[210:213], v224 offset:56320
	global_load_lds_dwordx4 v[226:227], off
	s_add_i32 m0, s20, 0x2000
	s_add_u32 s20, s22, 0x58080
	v_lshl_add_u64 v[226:227], v[228:229], 0, s[76:77]
	s_addc_u32 s21, s23, 0
	s_add_i32 s22, s48, s28
	global_load_lds_dwordx4 v[226:227], off
	v_lshl_add_u64 v[226:227], s[20:21], 0, v[158:159]
	s_mov_b32 m0, s22
	s_nop 0
	global_load_lds_dwordx4 v[226:227], off
	v_lshl_add_u64 v[226:227], s[20:21], 0, v[144:145]
	s_add_i32 m0, s22, 0x2000
	s_nop 0
	global_load_lds_dwordx4 v[226:227], off
	v_lshl_add_u64 v[226:227], v[230:231], 0, s[82:83]
	s_mov_b32 m0, s36
	s_nop 0
	global_load_lds_dwordx4 v[226:227], off
	v_lshl_add_u64 v[226:227], v[232:233], 0, s[82:83]
	s_mov_b32 m0, s37
	s_nop 0
	global_load_lds_dwordx4 v[226:227], off
	s_waitcnt vmcnt(8)
	s_waitcnt lgkmcnt(0)
	s_barrier
	s_setprio 1
	s_waitcnt lgkmcnt(0)
	v_mfma_f32_16x16x32_bf16 v[62:65], v[132:135], v[182:185], v[62:65]
	v_mfma_f32_16x16x32_bf16 v[58:61], v[140:143], v[182:185], v[58:61]
	v_mfma_f32_16x16x32_bf16 v[46:49], v[132:135], v[190:193], v[46:49]
	v_mfma_f32_16x16x32_bf16 v[42:45], v[140:143], v[190:193], v[42:45]
	v_mfma_f32_16x16x32_bf16 v[30:33], v[132:135], v[198:201], v[30:33]
	v_mfma_f32_16x16x32_bf16 v[26:29], v[140:143], v[198:201], v[26:29]
	v_mfma_f32_16x16x32_bf16 v[14:17], v[132:135], v[206:209], v[14:17]
	v_mfma_f32_16x16x32_bf16 v[10:13], v[140:143], v[206:209], v[10:13]
	v_mfma_f32_16x16x32_bf16 v[62:65], v[136:139], v[186:189], v[62:65]
	v_mfma_f32_16x16x32_bf16 v[58:61], v[154:157], v[186:189], v[58:61]
	v_mfma_f32_16x16x32_bf16 v[46:49], v[136:139], v[194:197], v[46:49]
	v_mfma_f32_16x16x32_bf16 v[42:45], v[154:157], v[194:197], v[42:45]
	v_mfma_f32_16x16x32_bf16 v[30:33], v[136:139], v[202:205], v[30:33]
	v_mfma_f32_16x16x32_bf16 v[26:29], v[154:157], v[202:205], v[26:29]
	v_mfma_f32_16x16x32_bf16 v[14:17], v[136:139], v[210:213], v[14:17]
	v_mfma_f32_16x16x32_bf16 v[10:13], v[154:157], v[210:213], v[10:13]
	s_setprio 0
	s_setprio 1
	v_mfma_f32_16x16x32_bf16 v[54:57], v[166:169], v[182:185], v[54:57]
	v_mfma_f32_16x16x32_bf16 v[50:53], v[174:177], v[182:185], v[50:53]
	v_mfma_f32_16x16x32_bf16 v[38:41], v[166:169], v[190:193], v[38:41]
	v_mfma_f32_16x16x32_bf16 v[34:37], v[174:177], v[190:193], v[34:37]
	v_mfma_f32_16x16x32_bf16 v[22:25], v[166:169], v[198:201], v[22:25]
	v_mfma_f32_16x16x32_bf16 v[18:21], v[174:177], v[198:201], v[18:21]
	v_mfma_f32_16x16x32_bf16 v[6:9], v[166:169], v[206:209], v[6:9]
	v_mfma_f32_16x16x32_bf16 v[2:5], v[174:177], v[206:209], v[2:5]
	v_mfma_f32_16x16x32_bf16 v[54:57], v[170:173], v[186:189], v[54:57]
	v_mfma_f32_16x16x32_bf16 v[50:53], v[178:181], v[186:189], v[50:53]
	v_mfma_f32_16x16x32_bf16 v[38:41], v[170:173], v[194:197], v[38:41]
	v_mfma_f32_16x16x32_bf16 v[34:37], v[178:181], v[194:197], v[34:37]
	v_mfma_f32_16x16x32_bf16 v[22:25], v[170:173], v[202:205], v[22:25]
	v_mfma_f32_16x16x32_bf16 v[18:21], v[178:181], v[202:205], v[18:21]
	v_mfma_f32_16x16x32_bf16 v[6:9], v[170:173], v[210:213], v[6:9]
	v_mfma_f32_16x16x32_bf16 v[2:5], v[178:181], v[210:213], v[2:5]
	s_setprio 0
	s_barrier
	s_add_i32 s46, s46, 2
	s_add_u32 s42, s42, 0x100
	s_addc_u32 s43, s43, 0
	s_cmpk_gt_u32 s46, 0x55
	s_mov_b64 s[20:21], s[2:3]
	s_cbranch_scc0 .LBB0_1048
	s_and_b64 vcc, exec, s[16:17]
	s_cbranch_vccz .LBB0_1051
	s_barrier

; __global__ void __launch_bounds__(NWAVES * 64, 2) hybrid_fwd(Args args) {
	.amdhsa_kernel _Z10hybrid_fwd4Args
		.amdhsa_group_segment_fixed_size 0
		.amdhsa_private_segment_fixed_size 0
		.amdhsa_kernarg_size 472
		.amdhsa_user_sgpr_count 2
		.amdhsa_user_sgpr_dispatch_ptr 0
		.amdhsa_user_sgpr_queue_ptr 0
		.amdhsa_user_sgpr_kernarg_segment_ptr 1
		.amdhsa_user_sgpr_dispatch_id 0
		.amdhsa_user_sgpr_kernarg_preload_length 0
		.amdhsa_user_sgpr_kernarg_preload_offset 0
		.amdhsa_user_sgpr_private_segment_size 0
		.amdhsa_uses_dynamic_stack 0
		.amdhsa_enable_private_segment 0
		.amdhsa_system_sgpr_workgroup_id_x 1
		.amdhsa_system_sgpr_workgroup_id_y 0
		.amdhsa_system_sgpr_workgroup_id_z 0
		.amdhsa_system_sgpr_workgroup_info 0
		.amdhsa_system_vgpr_workitem_id 0
		.amdhsa_next_free_vgpr 256
		.amdhsa_next_free_sgpr 102
		.amdhsa_accum_offset 256
		.amdhsa_reserve_vcc 1
		.amdhsa_float_round_mode_32 0
		.amdhsa_float_round_mode_16_64 0
		.amdhsa_float_denorm_mode_32 3
		.amdhsa_float_denorm_mode_16_64 3
		.amdhsa_dx10_clamp 1
		.amdhsa_ieee_mode 1
		.amdhsa_fp16_overflow 0
		.amdhsa_tg_split 0
		.amdhsa_exception_fp_ieee_invalid_op 0
		.amdhsa_exception_fp_denorm_src 0
		.amdhsa_exception_fp_ieee_div_zero 0
		.amdhsa_exception_fp_ieee_overflow 0
		.amdhsa_exception_fp_ieee_underflow 0
		.amdhsa_exception_fp_ieee_inexact 0
		.amdhsa_exception_int_div_zero 0
	.end_amdhsa_kernel

; __global__ void __launch_bounds__(NWAVES * 64, 2) hybrid_fwd(Args args) {
.Lfunc_end0:
	.size	_Z10hybrid_fwd4Args, .Lfunc_end0-_Z10hybrid_fwd4Args
	.set _Z10hybrid_fwd4Args.num_vgpr, 256
	.set _Z10hybrid_fwd4Args.num_agpr, 0
	.set _Z10hybrid_fwd4Args.numbered_sgpr, 100
	.set _Z10hybrid_fwd4Args.num_named_barrier, 0
	.set _Z10hybrid_fwd4Args.private_seg_size, 0
	.set _Z10hybrid_fwd4Args.uses_vcc, 1
	.set _Z10hybrid_fwd4Args.uses_flat_scratch, 0
	.set _Z10hybrid_fwd4Args.has_dyn_sized_stack, 0
	.set _Z10hybrid_fwd4Args.has_recursion, 0
	.set _Z10hybrid_fwd4Args.has_indirect_call, 0

; __global__ void __launch_bounds__(NWAVES * 64, 2) hybrid_fwd(Args args) {
amdhsa.kernels:
  - .agpr_count:     0
    .args:
      - .offset:         0
        .size:           216
        .value_kind:     by_value
      - .offset:         216
        .size:           4
        .value_kind:     hidden_block_count_x
      - .offset:         220
        .size:           4
        .value_kind:     hidden_block_count_y
      - .offset:         224
        .size:           4
        .value_kind:     hidden_block_count_z
      - .offset:         228
        .size:           2
        .value_kind:     hidden_group_size_x
      - .offset:         230
        .size:           2
        .value_kind:     hidden_group_size_y
      - .offset:         232
        .size:           2
        .value_kind:     hidden_group_size_z
      - .offset:         234
        .size:           2
        .value_kind:     hidden_remainder_x
      - .offset:         236
        .size:           2
        .value_kind:     hidden_remainder_y
      - .offset:         238
        .size:           2
        .value_kind:     hidden_remainder_z
      - .offset:         256
        .size:           8
        .value_kind:     hidden_global_offset_x
      - .offset:         264
        .size:           8
        .value_kind:     hidden_global_offset_y
      - .offset:         272
        .size:           8
        .value_kind:     hidden_global_offset_z
      - .offset:         280
        .size:           2
        .value_kind:     hidden_grid_dims
      - .offset:         336
        .size:           4
        .value_kind:     hidden_dynamic_lds_size
    .group_segment_fixed_size: 0
    .kernarg_segment_align: 8
    .kernarg_segment_size: 472
    .language:       OpenCL C
    .language_version:
      - 2
      - 0
    .max_flat_workgroup_size: 512
    .name:           _Z10hybrid_fwd4Args
    .private_segment_fixed_size: 0
    .sgpr_count:     108
    .sgpr_spill_count: 463
    .symbol:         _Z10hybrid_fwd4Args.kd
    .uniform_work_group_size: 1
    .uses_dynamic_stack: false
    .vgpr_count:     256
    .vgpr_spill_count: 0
    .wavefront_size: 64
